# scan: during a unit's last chunk wave 0 touches the next unit's first-chunk Q|K|V tiles (ticket known one unit ahead) so its first loads hit L2; code placed in the unreachable padding, placement elsew
# speedup vs baseline: 1.0025x; 1.0010x over previous
.Lpf_a:
	v_readfirstlane_b32 s26, v184
	s_cmp_lt_u32 s26, 64
	s_cbranch_scc0 .Lpf_a_end
	v_readfirstlane_b32 s27, v255
	s_cmp_ge_u32 s27, 0x400
	s_cbranch_scc1 .Lpf_a_end
	s_and_b32 s58, s27, 0x1ff
	s_lshr_b32 s59, s58, 4
	s_lshl_b32 s59, s59, 7
	s_cmp_lt_u32 s27, 0x200
	s_cbranch_scc0 .Lpf_a_ssd
	s_mul_i32 s60, s59, 0x3000
	s_bfe_u32 s61, s58, 0x20002
	s_lshl_b32 s61, s61, 8
	s_and_b32 s72, s58, 3
	s_lshl_b32 s72, s72, 7
	s_lshl_b32 s73, s61, 1
	s_add_u32 s72, s72, s73
	s_add_u32 s72, s72, 0x800
	s_add_u32 s73, s61, 0x400
	s_movk_i32 s98, 0x3000
	s_mov_b32 s99, 0x8500000
	s_branch .Lpf_a_go
.Lpf_a_ssd:
	s_lshl_b32 s60, s59, 12
	s_and_b32 s61, s58, 15
	s_lshl_b32 s72, s61, 7
	s_lshr_b32 s61, s61, 2
	s_lshl_b32 s61, s61, 8
	s_add_u32 s73, s61, 0x800
	s_add_u32 s61, s61, 0xc00
	s_movk_i32 s98, 0x1000
	s_mov_b32 s99, 0xe500000
.Lpf_a_go:
	s_add_u32 s26, s28, s99
	s_addc_u32 s27, s29, 0
	s_add_u32 s26, s26, s60
	s_addc_u32 s27, s27, 0
	v_mbcnt_hi_u32_b32 v46, -1, v185
	v_lshrrev_b32_e32 v45, 1, v46
	v_and_b32_e32 v47, 1, v46
	v_mul_lo_u32 v45, v45, s98
	v_mul_lo_u32 v46, v46, s98
	v_lshl_add_u32 v45, v47, 7, v45
	s_lshl_b32 s100, s98, 5
	s_add_u32 s58, s26, s61
	s_addc_u32 s59, s27, 0
	global_load_dword v44, v45, s[58:59]
	s_add_u32 s58, s58, s100
	s_addc_u32 s59, s59, 0
	global_load_dword v44, v45, s[58:59]
	s_add_u32 s58, s58, s100
	s_addc_u32 s59, s59, 0
	global_load_dword v44, v45, s[58:59]
	s_add_u32 s58, s58, s100
	s_addc_u32 s59, s59, 0
	global_load_dword v44, v45, s[58:59]
	s_add_u32 s58, s26, s73
	s_addc_u32 s59, s27, 0
	global_load_dword v44, v45, s[58:59]
	s_add_u32 s58, s58, s100
	s_addc_u32 s59, s59, 0
	global_load_dword v44, v45, s[58:59]
	s_add_u32 s58, s58, s100
	s_addc_u32 s59, s59, 0
	global_load_dword v44, v45, s[58:59]
	s_add_u32 s58, s58, s100
	s_addc_u32 s59, s59, 0
	global_load_dword v44, v45, s[58:59]
	s_add_u32 s58, s26, s72
	s_addc_u32 s59, s27, 0
	global_load_dword v44, v46, s[58:59]
	s_lshl_b32 s100, s100, 1
	s_add_u32 s58, s58, s100
	s_addc_u32 s59, s59, 0
	global_load_dword v44, v46, s[58:59]

.Lpf_b_end:
	s_branch .LBB0_631
	s_nop 0
	s_nop 0
	s_nop 0
	s_nop 0
	s_nop 0
	s_nop 0
	s_nop 0
	s_nop 0
	s_nop 0
	s_nop 0
	s_nop 0
	s_nop 0
	s_nop 0
	s_nop 0
	s_nop 0
	s_nop 0
	s_nop 0
	s_nop 0
	s_nop 0
	s_nop 0
	s_nop 0
	s_nop 0
	s_nop 0
	s_nop 0
	s_nop 0
	s_nop 0
	s_nop 0
	s_nop 0
	s_nop 0
	s_nop 0
	s_nop 0
	s_nop 0
	s_nop 0
	s_nop 0
	s_nop 0
	s_nop 0
	s_nop 0
	s_nop 0
	s_nop 0
	s_nop 0
	s_nop 0
	s_nop 0
	s_nop 0
	s_nop 0
	s_nop 0
	s_nop 0
	s_nop 0
	s_nop 0
	s_nop 0
	s_nop 0
	s_nop 0
	s_nop 0
	s_nop 0
	s_nop 0
	s_nop 0
	s_nop 0
	s_nop 0
	s_nop 0
	s_nop 0
	s_nop 0
	s_nop 0
	s_nop 0
	s_nop 0
	s_nop 0
	s_nop 0
	s_nop 0
	s_nop 0
	s_nop 0
	s_nop 0
	s_nop 0
	s_nop 0
	s_nop 0
	s_nop 0
	s_nop 0
	s_nop 0
	s_nop 0
	s_nop 0
	s_nop 0
	s_nop 0
	s_nop 0
	s_nop 0
	s_nop 0
	s_nop 0
	s_nop 0
	s_nop 0
	s_nop 0
	s_nop 0
	s_nop 0
	s_nop 0
	s_nop 0
	s_nop 0
	s_nop 0
	s_nop 0
	s_nop 0
	s_nop 0
	s_nop 0
	s_nop 0
	s_nop 0
	s_nop 0
	s_nop 0
	s_nop 0
	s_nop 0
	s_nop 0
	s_nop 0
	s_nop 0
	s_nop 0
	s_nop 0
	s_nop 0
	s_nop 0
	s_nop 0
	s_nop 0
	s_nop 0
	s_nop 0
	s_nop 0
	s_nop 0
	s_nop 0
	s_nop 0
	s_nop 0
	s_nop 0
	s_nop 0
	s_nop 0
	s_nop 0
	s_nop 0
	s_nop 0
	s_nop 0
	s_nop 0
	s_nop 0
	s_nop 0
	s_nop 0
	s_nop 0
	s_nop 0
	s_nop 0
	s_nop 0
	s_nop 0
	s_nop 0
	s_nop 0
	s_nop 0
	s_nop 0
	s_nop 0
	s_nop 0
	s_nop 0
	s_nop 0
	s_nop 0
	s_nop 0
	s_nop 0
	s_nop 0
	s_nop 0
	s_nop 0
	s_nop 0
	s_nop 0
	s_nop 0
	s_nop 0
	s_nop 0
	s_nop 0
	s_nop 0
	s_nop 0
	s_nop 0
	s_nop 0
	s_nop 0
	s_nop 0
	s_nop 0
	s_nop 0
	s_nop 0
	s_nop 0
	s_nop 0
	s_nop 0
	s_nop 0
	s_nop 0
	s_nop 0
	s_nop 0
	s_nop 0
	s_nop 0
	s_nop 0
	s_nop 0
	s_nop 0
	s_nop 0
	s_nop 0
	s_nop 0
	s_nop 0
	s_nop 0
	s_nop 0
	s_nop 0
	s_nop 0
	s_nop 0
	s_nop 0
	s_nop 0
	s_nop 0
	s_nop 0
	s_nop 0
	s_nop 0
	s_nop 0
	s_nop 0
	s_nop 0
	s_nop 0
	s_nop 0
	s_nop 0
	s_nop 0
	s_nop 0
	s_nop 0
	s_nop 0
	s_nop 0
	s_nop 0
	s_nop 0
	s_nop 0
	s_nop 0
	s_nop 0
	s_nop 0
	s_nop 0
	s_nop 0
	s_nop 0
	s_nop 0
	s_nop 0
	s_nop 0
	s_nop 0
	s_nop 0
	s_nop 0
	s_nop 0
	s_nop 0
	s_nop 0
	s_nop 0
	s_nop 0
	s_nop 0
	s_nop 0
	s_nop 0
	s_nop 0
	s_nop 0
	s_nop 0
	s_nop 0
	s_nop 0
	s_nop 0
	s_nop 0
	s_nop 0
	s_nop 0
	s_nop 0
	s_nop 0
	s_nop 0
	s_nop 0
	s_nop 0
	s_nop 0
	s_nop 0
	s_nop 0
	s_nop 0
	s_nop 0
	s_nop 0
	s_nop 0
	s_nop 0
	s_nop 0
	s_nop 0
	s_nop 0
	s_nop 0
	s_nop 0
	s_nop 0
	s_nop 0
	s_nop 0
	s_nop 0
	s_nop 0
	s_nop 0
	s_nop 0
	s_nop 0
	s_nop 0
	s_nop 0
	s_nop 0
	s_nop 0
	s_nop 0
	s_nop 0
	s_nop 0
	s_nop 0
	s_nop 0
	s_nop 0
	s_nop 0
	s_nop 0
	s_nop 0
	s_nop 0
	s_nop 0
	s_nop 0
	s_nop 0
	s_nop 0
	s_nop 0
	s_nop 0
	s_nop 0
	s_nop 0
	s_nop 0
	s_nop 0
	s_nop 0
	s_nop 0
	s_nop 0
	s_nop 0
	s_nop 0
	s_nop 0
	s_nop 0
	s_nop 0
	s_nop 0
	s_nop 0
	s_nop 0
	s_nop 0
	s_nop 0
	s_nop 0
	s_nop 0
	s_nop 0
	s_nop 0
	s_nop 0
	s_nop 0
	s_nop 0
	s_nop 0
	s_nop 0
	s_nop 0
	s_nop 0
	s_nop 0
	s_nop 0
	s_nop 0
	s_nop 0
	s_nop 0
	s_nop 0
	s_nop 0
	s_nop 0
	s_nop 0
	s_nop 0
	s_nop 0
	s_nop 0
	s_nop 0
	s_nop 0
	s_nop 0
	s_nop 0
	s_nop 0
	s_nop 0
	s_nop 0
	s_nop 0
	s_nop 0
	s_nop 0
	s_nop 0
	s_nop 0
	s_nop 0
	s_nop 0
	s_nop 0
	s_nop 0
	s_nop 0
	s_nop 0
	s_nop 0
	s_nop 0
	s_nop 0
	s_nop 0
	s_nop 0
	s_nop 0
	s_nop 0
	s_nop 0
	s_nop 0
	s_nop 0
	s_nop 0
	s_nop 0
	s_nop 0
	s_nop 0
	s_nop 0
	s_nop 0
	s_nop 0
	s_nop 0
	s_nop 0
	s_nop 0
	s_nop 0
	s_nop 0
	s_nop 0
	s_nop 0
	s_nop 0
	s_nop 0
	s_nop 0
	s_nop 0
	s_nop 0
	s_nop 0
	s_nop 0
	s_nop 0
	s_nop 0
	s_nop 0
	s_nop 0
	s_nop 0
	s_nop 0
	s_nop 0
	s_nop 0
	s_nop 0
	s_nop 0
	s_nop 0
	s_nop 0
	s_nop 0
	s_nop 0
	s_nop 0
	s_nop 0
	s_nop 0
	s_nop 0
	s_nop 0
	s_nop 0
	s_nop 0
	s_nop 0
	s_nop 0
	s_nop 0
	s_nop 0
	s_nop 0
	s_nop 0
	s_nop 0
	s_nop 0
	s_nop 0
	s_nop 0
	s_nop 0
	s_nop 0
	s_nop 0
	s_nop 0
	s_nop 0
	s_nop 0
	s_nop 0
	s_nop 0
	s_nop 0
	s_nop 0
	s_nop 0
	s_nop 0
	s_nop 0
	s_nop 0
	s_nop 0
	s_nop 0
	s_nop 0
	s_nop 0
	s_nop 0
	s_nop 0
	s_nop 0
	s_nop 0
	s_nop 0
	s_nop 0
	s_nop 0
	s_nop 0
	s_nop 0
	s_nop 0
	s_nop 0
	s_nop 0
	s_nop 0
	s_nop 0
	s_nop 0
	s_nop 0
	s_nop 0
	s_nop 0
	s_nop 0
	s_nop 0
	s_nop 0
	s_nop 0
	s_nop 0
	s_nop 0
	s_nop 0
	s_nop 0
	s_nop 0
	s_nop 0
	s_nop 0
	s_nop 0
	s_nop 0
	s_nop 0
	s_nop 0
	s_nop 0
	s_nop 0
	s_nop 0
	s_nop 0
	s_nop 0
	s_nop 0
	s_nop 0
	s_nop 0
	s_nop 0
	s_nop 0
	s_nop 0
	s_nop 0
	s_nop 0
	s_nop 0
	s_nop 0
	s_nop 0
	s_nop 0
	s_nop 0
	s_nop 0
	s_nop 0
	s_nop 0
	s_nop 0
	s_nop 0
	s_nop 0
	s_nop 0
	s_nop 0
	s_nop 0
	s_nop 0
	s_nop 0
	s_nop 0
	s_nop 0
	s_nop 0
	s_nop 0
	s_nop 0
	s_nop 0
	s_nop 0
	s_nop 0
	s_nop 0
	s_nop 0
	s_nop 0
	s_nop 0
	s_nop 0
	s_nop 0
	s_nop 0
	s_nop 0
	s_nop 0
	s_nop 0
	s_nop 0
	s_nop 0
	s_nop 0
	s_nop 0
	s_nop 0
	s_nop 0
	s_nop 0
	s_nop 0
	s_nop 0
	s_nop 0
	s_nop 0
	s_nop 0
	s_nop 0
	s_nop 0
	s_nop 0
	s_nop 0
	s_nop 0
	s_nop 0
	s_nop 0
	s_nop 0
	s_nop 0
	s_nop 0
	s_nop 0
	s_nop 0
	s_nop 0
	s_nop 0
	s_nop 0
	s_nop 0
	s_nop 0
	s_nop 0
	s_nop 0
	s_nop 0
	s_nop 0
	s_nop 0
	s_nop 0
	s_nop 0
	s_nop 0
	s_nop 0
	s_nop 0
	s_nop 0
	s_nop 0
	s_nop 0
	s_nop 0
	s_nop 0
	s_nop 0
	s_nop 0
	s_nop 0
	s_nop 0
	s_nop 0
	s_nop 0
	s_nop 0
	s_nop 0
	s_nop 0
	s_nop 0
	s_nop 0
	s_nop 0
	s_nop 0
	s_nop 0
	s_nop 0
	s_nop 0
	s_nop 0
	s_nop 0
	s_nop 0
	s_nop 0
	s_nop 0
	s_nop 0
	s_nop 0
	s_nop 0
	s_nop 0
	s_nop 0
	s_nop 0
	s_nop 0
	s_nop 0
	s_nop 0
	s_nop 0
	s_nop 0
	s_nop 0
	s_nop 0
	s_nop 0
	s_nop 0
	s_nop 0
	s_nop 0
	s_nop 0
	s_nop 0
	s_nop 0
	s_nop 0
	s_nop 0
	s_nop 0
	s_nop 0
	s_nop 0
	s_nop 0
	s_nop 0
	s_nop 0
	s_nop 0
	s_nop 0
	s_nop 0
	s_nop 0
	s_nop 0
	s_nop 0
	s_nop 0
	s_nop 0
	s_nop 0
	s_nop 0
	s_nop 0
	s_nop 0
	s_nop 0
	s_nop 0
	s_nop 0
	s_nop 0
	s_nop 0
	s_nop 0
	s_nop 0
	s_nop 0
	s_nop 0
	s_nop 0
	s_nop 0
	s_nop 0
	s_nop 0
	s_nop 0
	s_nop 0
	s_nop 0
	s_nop 0
	s_nop 0
	s_nop 0
	s_nop 0
	s_nop 0
	s_nop 0
	s_nop 0
	s_nop 0
	s_nop 0
	s_nop 0
	s_nop 0
	s_nop 0
	s_nop 0
	s_nop 0
	s_nop 0
	s_nop 0
	s_nop 0
	s_nop 0
	s_nop 0
	s_nop 0
	s_nop 0
	s_nop 0
	s_nop 0
	s_nop 0
	s_nop 0
	s_nop 0
	s_nop 0
	s_nop 0
	s_nop 0
	s_nop 0
	s_nop 0
	s_nop 0
	s_nop 0
	s_nop 0
	s_nop 0
	s_nop 0
	s_nop 0
	s_nop 0
	s_nop 0
	s_nop 0
	s_nop 0
	s_nop 0
	s_nop 0
	s_nop 0
	s_nop 0
	s_nop 0
	s_nop 0
	s_nop 0
	s_nop 0
	s_nop 0
	s_nop 0
	s_nop 0
	s_nop 0
	s_nop 0
	s_nop 0
	s_nop 0
	s_nop 0
	s_nop 0
	s_nop 0
	s_nop 0
	s_nop 0
	s_nop 0
	s_nop 0
	s_nop 0
	s_nop 0
	s_nop 0
	s_nop 0
	s_nop 0
	s_nop 0
	s_nop 0
	s_nop 0
	s_nop 0
	s_nop 0
	s_nop 0
	s_nop 0
	s_nop 0
	s_nop 0
	s_nop 0
	s_nop 0
	s_nop 0
	s_nop 0
	s_nop 0
	s_nop 0
	s_nop 0
	s_nop 0
	s_nop 0
	s_nop 0
	s_nop 0
	s_nop 0
	s_nop 0
	s_nop 0
	s_nop 0
	s_nop 0
	s_nop 0
	s_nop 0
	s_nop 0
	s_nop 0
	s_nop 0
	s_nop 0
	s_nop 0
	s_nop 0
	s_nop 0
	s_nop 0
	s_nop 0
	s_nop 0
	s_nop 0
	s_nop 0
	s_nop 0
	s_nop 0
	s_nop 0
	s_nop 0
	s_nop 0
	s_nop 0
	s_nop 0
	s_nop 0
	s_nop 0
	s_nop 0
	s_nop 0
	s_nop 0
	s_nop 0
	s_nop 0
	s_nop 0
	s_nop 0
	s_nop 0
	s_nop 0
	s_nop 0
	s_nop 0
	s_nop 0
	s_nop 0
	s_nop 0
	s_nop 0
	s_nop 0
	s_nop 0
	s_nop 0
	s_nop 0
	s_nop 0
	s_nop 0
	s_nop 0
	s_nop 0
	s_nop 0
	s_nop 0
	s_nop 0
	s_nop 0
	s_nop 0
	s_nop 0
	s_nop 0
	s_nop 0
	s_nop 0
	s_nop 0
	s_nop 0
	s_nop 0
	s_nop 0
	s_nop 0
	s_nop 0
	s_nop 0
	s_nop 0
	s_nop 0
	s_nop 0
	s_nop 0
	s_nop 0
	s_nop 0
	s_nop 0
	s_nop 0
	s_nop 0
	s_nop 0
	s_nop 0
	s_nop 0
	s_nop 0
	s_nop 0
	s_nop 0
	s_nop 0
	s_nop 0
	s_nop 0
	s_nop 0
	s_nop 0
	s_nop 0
	s_nop 0
	s_nop 0
	s_nop 0
	s_nop 0
	s_nop 0
	s_nop 0
	s_nop 0
	s_nop 0
	s_nop 0
	s_nop 0
	s_nop 0
	s_nop 0
	s_nop 0
	s_nop 0
	s_nop 0
	s_nop 0
	s_nop 0
	s_nop 0
	s_nop 0
	s_nop 0
	s_nop 0
	s_nop 0
	s_nop 0
	s_nop 0
	s_nop 0
	s_nop 0
	s_nop 0
	s_nop 0
	s_nop 0
	s_nop 0
	s_nop 0
	s_nop 0
	s_nop 0
	s_nop 0
	s_nop 0
	s_nop 0
	s_nop 0
	s_nop 0
	s_nop 0
	s_nop 0
	s_nop 0
	s_nop 0
	s_nop 0
	s_nop 0
	s_nop 0
	s_nop 0
	s_nop 0
	s_nop 0
	s_nop 0
	s_nop 0
	s_nop 0
	s_nop 0
	s_nop 0
	s_nop 0
	s_nop 0
	s_nop 0
	s_nop 0
	s_nop 0
	s_nop 0
	s_nop 0
	s_nop 0
	s_nop 0
	s_nop 0
	s_nop 0
	s_nop 0
	s_nop 0
	s_nop 0
	s_nop 0
	s_nop 0
	s_nop 0
	s_nop 0
	s_nop 0
	s_nop 0
	s_nop 0
	s_nop 0
	s_nop 0
	s_nop 0
	s_nop 0
	s_nop 0
	s_nop 0
	s_nop 0
	s_nop 0
	s_nop 0
	s_nop 0
	s_nop 0
	s_nop 0
	s_nop 0
	s_nop 0
	s_nop 0
	s_nop 0
	s_nop 0
	s_nop 0
	s_nop 0
	s_nop 0
	s_nop 0
	s_nop 0
	s_nop 0
	s_nop 0
	s_nop 0
	s_nop 0
	s_nop 0
	s_nop 0
	s_nop 0
	s_nop 0
	s_nop 0
	s_nop 0
	s_nop 0
	s_nop 0
	s_nop 0
	s_nop 0
	s_nop 0
	s_nop 0
	s_nop 0
	s_nop 0
	s_nop 0
	s_nop 0
	s_nop 0
	s_nop 0
	s_nop 0
	s_nop 0
	s_nop 0
	s_nop 0
	s_nop 0
	s_nop 0
	s_nop 0
	s_nop 0
	s_nop 0
	s_nop 0
	s_nop 0
	s_nop 0
	s_nop 0
	s_nop 0
	s_nop 0
	s_nop 0
	s_nop 0
	s_nop 0
	s_nop 0
	s_nop 0
	s_nop 0
	s_nop 0
	s_nop 0
	s_nop 0
	s_nop 0
	s_nop 0
	s_nop 0
	s_nop 0
	s_nop 0
	s_nop 0
	s_nop 0
	s_nop 0
	s_nop 0
	s_nop 0
	s_nop 0
	s_nop 0
	s_nop 0
	s_nop 0
	s_nop 0
	s_nop 0
	s_nop 0
	s_nop 0
	s_nop 0
	s_nop 0
	s_nop 0
	s_nop 0
	s_nop 0
	s_nop 0
	s_nop 0
	s_nop 0
	s_nop 0
	s_nop 0
	s_nop 0
	s_nop 0
	s_nop 0
	s_nop 0
	s_nop 0
	s_nop 0
	s_nop 0
	s_nop 0
	s_nop 0
	s_nop 0
	s_nop 0
	s_nop 0
	s_nop 0
	s_nop 0
	s_nop 0
	s_nop 0
	s_nop 0
	s_nop 0
	s_nop 0
	s_nop 0
	s_nop 0
	s_nop 0
	s_nop 0
	s_nop 0
	s_nop 0
	s_nop 0
	s_nop 0
	s_nop 0
	s_nop 0
	s_nop 0
	s_nop 0
	s_nop 0
	s_nop 0
	s_nop 0
	s_nop 0
	s_nop 0
	s_nop 0
	s_nop 0
	s_nop 0
	s_nop 0
	s_nop 0
	s_nop 0
	s_nop 0
	s_nop 0
	s_nop 0
	s_nop 0
	s_nop 0
	s_nop 0
	s_nop 0
	s_nop 0
	s_nop 0
	s_nop 0
	s_nop 0
	s_nop 0
	s_nop 0
	s_nop 0
	s_nop 0
	s_nop 0
	s_nop 0
	s_nop 0
	s_nop 0
	s_nop 0
	s_nop 0
	s_nop 0
	s_nop 0
	s_nop 0
	s_nop 0
	s_nop 0
	s_nop 0
	s_nop 0
	s_nop 0
	s_nop 0
	s_nop 0
	s_nop 0
	s_nop 0
	s_nop 0
	s_nop 0
	s_nop 0
	s_nop 0
	s_nop 0
	s_nop 0
	s_nop 0
	s_nop 0
	s_nop 0
	s_nop 0
	s_nop 0
	s_nop 0
	s_nop 0
	s_nop 0
	s_nop 0
	s_nop 0
	s_nop 0
	s_nop 0
	s_nop 0
	s_nop 0
	s_nop 0
	s_nop 0
	s_nop 0
	s_nop 0
	s_nop 0
	s_nop 0
	s_nop 0
	s_nop 0
	s_nop 0
	s_nop 0
	s_nop 0
	s_nop 0
	s_nop 0
	s_nop 0
	s_nop 0
	s_nop 0
	s_nop 0
	s_nop 0
	s_nop 0
	s_nop 0
	s_nop 0
	s_nop 0
	s_nop 0
	s_nop 0
	s_nop 0
	s_nop 0
	s_nop 0
	s_nop 0
	s_nop 0
	s_nop 0
	s_nop 0
	s_nop 0
	s_nop 0
	s_nop 0
	s_nop 0
	s_nop 0
	s_nop 0
	s_nop 0
	s_nop 0
	s_nop 0
	s_nop 0
	s_nop 0
	s_nop 0
	s_nop 0
	s_nop 0
	s_nop 0
	s_nop 0
	s_nop 0
	s_nop 0
	s_nop 0
	s_nop 0
	s_nop 0
	s_nop 0
	s_nop 0
	s_nop 0
	s_nop 0
	s_nop 0
	s_nop 0
	s_nop 0
	s_nop 0
	s_nop 0
	s_nop 0
	s_nop 0
	s_nop 0
	s_nop 0
	s_nop 0
	s_nop 0
	s_nop 0
	s_nop 0
	s_nop 0
	s_nop 0
	s_nop 0
	s_nop 0
	s_nop 0
	s_nop 0
	s_nop 0
	s_nop 0
	s_nop 0
	s_nop 0
	s_nop 0
	s_nop 0
	s_nop 0
	s_nop 0
	s_nop 0
	s_nop 0
	s_nop 0
	s_nop 0
	s_nop 0
	s_nop 0
	s_nop 0
	s_nop 0
	s_nop 0
	s_nop 0
	s_nop 0
	s_nop 0
	s_nop 0
	s_nop 0
